# baseline (speedup 1.0000x reference)
; __device__ __forceinline__ void finishSM(f32x16& p0, f32x16& p1, float alpha, float& l_reg, bf16x8& pa0, bf16x8& pa1, bf16x8& pa2, bf16x8& pa3) {
; #pragma unroll
;     for (int r = 0; r < 16; ++r) p1[r] = __builtin_amdgcn_exp2f(p1[r]);
;     float ps = 0;
; #pragma unroll
;     for (int r = 0; r < 16; ++r) ps += p0[r];
; #pragma unroll
;     for (int r = 0; r < 16; ++r) ps += p1[r];
;     { auto rr = __builtin_amdgcn_permlane32_swap(__float_as_uint(ps), __float_as_uint(ps), false, false);
;       ps = __uint_as_float(rr[0]) + __uint_as_float(rr[1]); }
;     l_reg = l_reg * alpha + ps;
;     ...
;     PK4(p0, 0, pa0); PK4(p0, 8, pa1); PK4(p1, 0, pa2); PK4(p1, 8, pa3);
;     ...
; }
; template <int KB>
; __device__ __forceinline__ void qkt(f32x16& p0, f32x16& p1, const char* lds, int r32, int hi, const bf16x8* qr) {
;     p0 = f32x16{}; p1 = f32x16{};
;     const char* kb = lds + AO_K + KB * SHM_K + KSWZ(r32, hi * 16); const char* rb = lds + AO_R + KB * SHM_R + RSWZ(r32, hi * 16);
; #pragma unroll
;     for (int d0 = 0; d0 < 8; ++d0) { const char* a = kb + d0 * 32;
;         bf16x8 b0 = *reinterpret_cast<const bf16x8*>(a);
;         bf16x8 b1 = *reinterpret_cast<const bf16x8*>(a + 32 * KPITCH);
;         p0 = __builtin_amdgcn_mfma_f32_32x32x16_bf16(b0, qr[d0], p0, 0, 0, 0);
;         p1 = __builtin_amdgcn_mfma_f32_32x32x16_bf16(b1, qr[d0], p1, 0, 0, 0); }
; #pragma unroll
;     for (int d0 = 0; d0 < 4; ++d0) { const char* a = rb + d0 * 32;
;         bf16x8 b0 = *reinterpret_cast<const bf16x8*>(a);
;         bf16x8 b1 = *reinterpret_cast<const bf16x8*>(a + 32 * RPITCH);
;         p0 = __builtin_amdgcn_mfma_f32_32x32x16_bf16(b0, qr[8 + d0], p0, 0, 0, 0);
;         p1 = __builtin_amdgcn_mfma_f32_32x32x16_bf16(b1, qr[8 + d0], p1, 0, 0, 0); }
; }
; template <int VB>
; __device__ __forceinline__ void pv_tile(f32x16* o, int vb0, bf16x8 pa0, bf16x8 pa1, bf16x8 pa2, bf16x8 pa3) {
;     ...
;     PV_D0(0); PV_D0(1); PV_D0(2); PV_D0(3);
.LBB0_426:
	v_exp_f32_e32 v166, v166
	v_exp_f32_e32 v175, v175
	v_exp_f32_e32 v167, v167
	v_exp_f32_e32 v176, v176
	v_exp_f32_e32 v168, v168
	v_exp_f32_e32 v177, v177
	v_exp_f32_e32 v169, v169
	v_exp_f32_e32 v174, v174
	v_exp_f32_e32 v165, v165
	v_exp_f32_e32 v170, v170
	v_exp_f32_e32 v171, v171
	v_exp_f32_e32 v172, v172
	v_exp_f32_e32 v162, v162
	v_exp_f32_e32 v164, v164
	v_exp_f32_e32 v163, v163
	v_exp_f32_e32 v173, v173
	ds_read_b128 v[220:223], v200 offset:50176
	ds_read_b128 v[224:227], v200 offset:58880
	ds_read_b128 v[228:231], v200 offset:50208
	ds_read_b128 v[232:235], v200 offset:58912
	ds_read_b128 v[242:245], v200 offset:50240
	ds_read_b128 v[246:249], v200 offset:58944
	s_waitcnt lgkmcnt(4)
	v_mfma_f32_32x32x16_bf16 v[82:97], v[220:223], v[142:145], 0
	v_mfma_f32_32x32x16_bf16 v[66:81], v[224:227], v[142:145], 0
	ds_read_b128 v[220:223], v200 offset:50272
	ds_read_b128 v[224:227], v200 offset:58976
	s_waitcnt lgkmcnt(2)
	v_mfma_f32_32x32x16_bf16 v[82:97], v[228:231], v[138:141], v[82:97]
	v_mfma_f32_32x32x16_bf16 v[66:81], v[232:235], v[138:141], v[66:81]
	ds_read_b128 v[228:231], v200 offset:50304
	ds_read_b128 v[232:235], v200 offset:59008
	s_waitcnt lgkmcnt(2)
	v_mfma_f32_32x32x16_bf16 v[82:97], v[242:245], v[134:137], v[82:97]
	v_mfma_f32_32x32x16_bf16 v[66:81], v[246:249], v[134:137], v[66:81]
	ds_read_b128 v[242:245], v200 offset:50336
	ds_read_b128 v[246:249], v200 offset:59040
	s_waitcnt lgkmcnt(2)
	v_mfma_f32_32x32x16_bf16 v[82:97], v[220:223], v[130:133], v[82:97]
	v_mfma_f32_32x32x16_bf16 v[66:81], v[224:227], v[130:133], v[66:81]
	ds_read_b128 v[220:223], v200 offset:50368
	ds_read_b128 v[224:227], v200 offset:59072
	s_waitcnt lgkmcnt(2)
	v_mfma_f32_32x32x16_bf16 v[82:97], v[228:231], v[126:129], v[82:97]
	v_mfma_f32_32x32x16_bf16 v[66:81], v[232:235], v[126:129], v[66:81]
	ds_read_b128 v[228:231], v200 offset:50400
	ds_read_b128 v[232:235], v200 offset:59104
	s_waitcnt lgkmcnt(2)
	v_mfma_f32_32x32x16_bf16 v[82:97], v[242:245], v[122:125], v[82:97]
	v_mfma_f32_32x32x16_bf16 v[66:81], v[246:249], v[122:125], v[66:81]
	ds_read_b128 v[242:245], v205
	ds_read_b128 v[246:249], v205 offset:4608
	s_waitcnt lgkmcnt(2)
	v_mfma_f32_32x32x16_bf16 v[82:97], v[220:223], v[118:121], v[82:97]
	v_mfma_f32_32x32x16_bf16 v[66:81], v[224:227], v[118:121], v[66:81]
	ds_read_b128 v[220:223], v205 offset:32
	ds_read_b128 v[224:227], v205 offset:4640
	s_waitcnt lgkmcnt(2)
	v_mfma_f32_32x32x16_bf16 v[82:97], v[228:231], v[110:113], v[82:97]
	v_mfma_f32_32x32x16_bf16 v[66:81], v[232:235], v[110:113], v[66:81]
	ds_read_b128 v[228:231], v205 offset:64
	ds_read_b128 v[232:235], v205 offset:4672
	s_waitcnt lgkmcnt(2)
	v_mfma_f32_32x32x16_bf16 v[82:97], v[242:245], v[114:117], v[82:97]
	v_mfma_f32_32x32x16_bf16 v[66:81], v[246:249], v[114:117], v[66:81]
	ds_read_b128 v[242:245], v205 offset:96
	ds_read_b128 v[246:249], v205 offset:4704
	s_waitcnt lgkmcnt(2)
	v_mfma_f32_32x32x16_bf16 v[82:97], v[220:223], v[106:109], v[82:97]
	v_mfma_f32_32x32x16_bf16 v[66:81], v[224:227], v[106:109], v[66:81]
	s_waitcnt lgkmcnt(2)
	v_mfma_f32_32x32x16_bf16 v[82:97], v[228:231], v[102:105], v[82:97]
	v_mfma_f32_32x32x16_bf16 v[66:81], v[232:235], v[102:105], v[66:81]
	s_waitcnt lgkmcnt(0)
	v_mfma_f32_32x32x16_bf16 v[82:97], v[242:245], v[98:101], v[82:97]
	v_mfma_f32_32x32x16_bf16 v[66:81], v[246:249], v[98:101], v[66:81]
	v_add_f32_e32 v98, 0, v166
	v_add_f32_e32 v98, v175, v98
	v_add_f32_e32 v98, v167, v98
	v_add_f32_e32 v98, v176, v98
	v_add_f32_e32 v98, v168, v98
	v_add_f32_e32 v98, v177, v98
	v_add_f32_e32 v98, v169, v98
	v_add_f32_e32 v98, v174, v98
	v_add_f32_e32 v98, v165, v98
	v_add_f32_e32 v98, v170, v98
	v_add_f32_e32 v98, v171, v98
	v_add_f32_e32 v98, v172, v98
	v_exp_f32_e32 v108, v160
	v_add_f32_e32 v98, v162, v98
	v_exp_f32_e32 v109, v161
	v_add_f32_e32 v98, v164, v98
	v_exp_f32_e32 v110, v158
	v_add_f32_e32 v98, v163, v98
	v_exp_f32_e32 v111, v159
	v_add_f32_e32 v98, v173, v98
	v_exp_f32_e32 v112, v154
	v_add_f32_e32 v98, v108, v98
	v_exp_f32_e32 v113, v155
	v_add_f32_e32 v98, v109, v98
	v_exp_f32_e32 v114, v150
	v_add_f32_e32 v98, v110, v98
	v_exp_f32_e32 v115, v151
	v_add_f32_e32 v98, v111, v98
	v_exp_f32_e32 v116, v146
	v_add_f32_e32 v98, v112, v98
	v_exp_f32_e32 v117, v147
	v_add_f32_e32 v98, v113, v98
	v_exp_f32_e32 v118, v156
	v_add_f32_e32 v98, v114, v98
	v_exp_f32_e32 v119, v157
	v_add_f32_e32 v98, v115, v98
	v_exp_f32_e32 v120, v152
	v_add_f32_e32 v98, v116, v98
	v_exp_f32_e32 v121, v153
	v_add_f32_e32 v98, v117, v98
	v_exp_f32_e32 v122, v148
	v_add_f32_e32 v98, v118, v98
	v_exp_f32_e32 v123, v149
	v_add_f32_e32 v98, v119, v98
	v_add_f32_e32 v98, v120, v98
	v_add_f32_e32 v98, v121, v98
	v_add_f32_e32 v98, v122, v98
	v_add_f32_e32 v98, v123, v98
	v_mov_b32_e32 v99, v98
	s_nop 1
	v_permlane32_swap_b32_e32 v98, v99
	v_cvt_pk_bf16_f32 v100, v166, v175
	v_cvt_pk_bf16_f32 v101, v167, v176
	v_cvt_pk_bf16_f32 v102, v168, v177
	v_cvt_pk_bf16_f32 v103, v169, v174
	v_cvt_pk_bf16_f32 v104, v165, v170
	v_cvt_pk_bf16_f32 v105, v171, v172
	v_cvt_pk_bf16_f32 v106, v162, v164
	v_cvt_pk_bf16_f32 v107, v163, v173
	v_cvt_pk_bf16_f32 v108, v108, v109
	v_cvt_pk_bf16_f32 v109, v110, v111
	v_cvt_pk_bf16_f32 v110, v112, v113
	v_cvt_pk_bf16_f32 v111, v114, v115
	v_cvt_pk_bf16_f32 v112, v116, v117
	v_cvt_pk_bf16_f32 v113, v118, v119
	v_cvt_pk_bf16_f32 v114, v120, v121
	v_cvt_pk_bf16_f32 v115, v122, v123
	s_nop 0
	v_permlane32_swap_b32_e32 v100, v102
	v_permlane32_swap_b32_e32 v101, v103
	v_permlane32_swap_b32_e32 v104, v106
	v_permlane32_swap_b32_e32 v105, v107
	v_permlane32_swap_b32_e32 v108, v110
	v_permlane32_swap_b32_e32 v109, v111
	v_permlane32_swap_b32_e32 v112, v114
	v_permlane32_swap_b32_e32 v113, v115
	ds_read_b64_tr_b16 v[116:117], v194 offset:0
	ds_read_b64_tr_b16 v[118:119], v194 offset:0x800
	ds_read_b64_tr_b16 v[120:121], v194 offset:0x1000
	ds_read_b64_tr_b16 v[122:123], v194 offset:0x1800
	ds_read_b64_tr_b16 v[124:125], v194 offset:0x2000
	ds_read_b64_tr_b16 v[126:127], v194 offset:0x2800
	ds_read_b64_tr_b16 v[128:129], v194 offset:0x3000
	ds_read_b64_tr_b16 v[130:131], v194 offset:0x3800
	s_nop 0
	s_waitcnt lgkmcnt(6)
; __device__ __forceinline__ void mask_tile(f32x16& p0, f32x16& p1, int dq) {
;     const float NEG = -__builtin_inff();
; #pragma unroll
;     for (int r = 0; r < 16; ++r) { const int c = (r & 3) + 8 * (r >> 2);
;         if (dq - c < 0) p0[r] = NEG;
;         if (dq - c - 32 < 0) p1[r] = NEG; }
; }
; template <int VB>
; __device__ __forceinline__ void pv_tile(f32x16* o, int vb0, bf16x8 pa0, bf16x8 pa1, bf16x8 pa2, bf16x8 pa3) {
;     ...
;     PV_D0(0); PV_D0(1); PV_D0(2); PV_D0(3);
	v_mfma_f32_32x32x16_bf16 v[50:65], v[100:103], v[116:119], v[50:65]
	ds_read_b64_tr_b16 v[116:117], v194 offset:0x200
	ds_read_b64_tr_b16 v[118:119], v194 offset:0xa00
	s_waitcnt lgkmcnt(6)
	v_mfma_f32_32x32x16_bf16 v[50:65], v[104:107], v[120:123], v[50:65]
	ds_read_b64_tr_b16 v[120:121], v194 offset:0x1200
	ds_read_b64_tr_b16 v[122:123], v194 offset:0x1a00
	s_waitcnt lgkmcnt(6)
	v_mfma_f32_32x32x16_bf16 v[50:65], v[108:111], v[124:127], v[50:65]
	ds_read_b64_tr_b16 v[124:125], v194 offset:0x2200
	ds_read_b64_tr_b16 v[126:127], v194 offset:0x2a00
	s_waitcnt lgkmcnt(6)
	v_mfma_f32_32x32x16_bf16 v[50:65], v[112:115], v[128:131], v[50:65]
	ds_read_b64_tr_b16 v[128:129], v194 offset:0x3200
	ds_read_b64_tr_b16 v[130:131], v194 offset:0x3a00
	s_waitcnt lgkmcnt(6)
	v_mfma_f32_32x32x16_bf16 v[34:49], v[100:103], v[116:119], v[34:49]
	ds_read_b64_tr_b16 v[116:117], v194 offset:0x400
	ds_read_b64_tr_b16 v[118:119], v194 offset:0xc00
	s_waitcnt lgkmcnt(6)
	v_mfma_f32_32x32x16_bf16 v[34:49], v[104:107], v[120:123], v[34:49]
	ds_read_b64_tr_b16 v[120:121], v194 offset:0x1400
	ds_read_b64_tr_b16 v[122:123], v194 offset:0x1c00
	s_waitcnt lgkmcnt(6)
	v_mfma_f32_32x32x16_bf16 v[34:49], v[108:111], v[124:127], v[34:49]
	ds_read_b64_tr_b16 v[124:125], v194 offset:0x2400
	ds_read_b64_tr_b16 v[126:127], v194 offset:0x2c00
	s_waitcnt lgkmcnt(6)
	v_mfma_f32_32x32x16_bf16 v[34:49], v[112:115], v[128:131], v[34:49]
	ds_read_b64_tr_b16 v[128:129], v194 offset:0x3400
	ds_read_b64_tr_b16 v[130:131], v194 offset:0x3c00
	s_waitcnt lgkmcnt(6)
	v_mfma_f32_32x32x16_bf16 v[18:33], v[100:103], v[116:119], v[18:33]
	ds_read_b64_tr_b16 v[116:117], v194 offset:0x600
	ds_read_b64_tr_b16 v[118:119], v194 offset:0xe00
	s_waitcnt lgkmcnt(6)
	v_mfma_f32_32x32x16_bf16 v[18:33], v[104:107], v[120:123], v[18:33]
	ds_read_b64_tr_b16 v[120:121], v194 offset:0x1600
	ds_read_b64_tr_b16 v[122:123], v194 offset:0x1e00
	s_waitcnt lgkmcnt(6)
	v_mfma_f32_32x32x16_bf16 v[18:33], v[108:111], v[124:127], v[18:33]
	ds_read_b64_tr_b16 v[124:125], v194 offset:0x2600
	ds_read_b64_tr_b16 v[126:127], v194 offset:0x2e00
	s_waitcnt lgkmcnt(6)
	v_mfma_f32_32x32x16_bf16 v[18:33], v[112:115], v[128:131], v[18:33]
	ds_read_b64_tr_b16 v[128:129], v194 offset:0x3600
	ds_read_b64_tr_b16 v[130:131], v194 offset:0x3e00
	s_waitcnt lgkmcnt(6)
	v_mfma_f32_32x32x16_bf16 v[2:17], v[100:103], v[116:119], v[2:17]
	s_cmpk_lt_i32 s95, 0xff
	s_waitcnt lgkmcnt(4)
	v_mfma_f32_32x32x16_bf16 v[2:17], v[104:107], v[120:123], v[2:17]
	s_waitcnt lgkmcnt(2)
	v_mfma_f32_32x32x16_bf16 v[2:17], v[108:111], v[124:127], v[2:17]
	s_waitcnt lgkmcnt(0)
	v_mfma_f32_32x32x16_bf16 v[2:17], v[112:115], v[128:131], v[2:17]
	s_cbranch_scc0 .LBB0_428
	v_subrev_u32_e32 v100, s94, v197
	v_add_u32_e32 v100, 0xffffff40, v100
	v_cmp_gt_i32_e64 s[64:65], 26, v100
	v_cmp_gt_i32_e64 s[66:67], 27, v100
	v_cmp_gt_i32_e64 s[62:63], 25, v100
	s_and_b64 s[64:65], s[66:67], s[64:65]
	v_cmp_gt_i32_e64 s[60:61], 24, v100
	s_and_b64 s[62:63], s[64:65], s[62:63]
	v_cmp_gt_i32_e64 s[58:59], 19, v100
	s_and_b64 s[60:61], s[62:63], s[60:61]
	v_cmp_gt_i32_e64 s[56:57], 18, v100
	s_and_b64 s[58:59], s[60:61], s[58:59]
	v_cmp_gt_i32_e64 s[54:55], 17, v100
	s_and_b64 s[56:57], s[58:59], s[56:57]
	v_cmp_gt_i32_e64 s[52:53], 16, v100
	s_and_b64 s[54:55], s[56:57], s[54:55]
	v_cmp_gt_i32_e64 s[50:51], 11, v100
	s_and_b64 s[52:53], s[54:55], s[52:53]
	v_cmp_gt_i32_e64 s[48:49], 10, v100
	s_and_b64 s[50:51], s[52:53], s[50:51]
	v_cmp_gt_i32_e64 s[46:47], 9, v100
	s_and_b64 s[48:49], s[50:51], s[48:49]
	v_cmp_gt_i32_e64 s[44:45], 8, v100
	s_and_b64 s[46:47], s[48:49], s[46:47]
	v_cmp_gt_i32_e64 s[42:43], 3, v100
	s_and_b64 s[44:45], s[46:47], s[44:45]
	v_cmp_gt_i32_e64 s[40:41], 2, v100
	s_and_b64 s[42:43], s[44:45], s[42:43]
	v_cmp_gt_i32_e64 s[38:39], 1, v100
	s_and_b64 s[40:41], s[42:43], s[40:41]
	v_cmp_gt_i32_e64 s[36:37], 0, v100
	s_and_b64 s[38:39], s[40:41], s[38:39]
	s_and_b64 s[36:37], s[38:39], s[36:37]
	v_cmp_gt_i32_e64 s[34:35], 58, v100
	v_cndmask_b32_e64 v82, v82, v186, s[36:37]
	v_cmp_gt_i32_e64 s[36:37], 59, v100
	v_cmp_gt_i32_e64 s[30:31], 57, v100
	s_and_b64 s[34:35], s[36:37], s[34:35]
	v_cmp_gt_i32_e64 s[28:29], 56, v100
	s_and_b64 s[30:31], s[34:35], s[30:31]
	v_cmp_gt_i32_e64 s[26:27], 51, v100
	s_and_b64 s[28:29], s[30:31], s[28:29]
	v_cmp_gt_i32_e64 s[24:25], 50, v100
	s_and_b64 s[26:27], s[28:29], s[26:27]
	v_cmp_gt_i32_e64 s[22:23], 49, v100
	s_and_b64 s[24:25], s[26:27], s[24:25]
	v_cmp_gt_i32_e64 s[20:21], 48, v100
	s_and_b64 s[22:23], s[24:25], s[22:23]
	v_cmp_gt_i32_e64 s[18:19], 43, v100
	s_and_b64 s[20:21], s[22:23], s[20:21]
	v_cmp_gt_i32_e64 s[16:17], 42, v100
	s_and_b64 s[18:19], s[20:21], s[18:19]
	v_cmp_gt_i32_e64 s[14:15], 41, v100
	s_and_b64 s[16:17], s[18:19], s[16:17]
	v_cmp_gt_i32_e64 s[12:13], 40, v100
	s_and_b64 s[14:15], s[16:17], s[14:15]
	v_cmp_gt_i32_e64 s[10:11], 35, v100
	s_and_b64 s[12:13], s[14:15], s[12:13]
	v_cmp_gt_i32_e64 s[8:9], 34, v100
	s_and_b64 s[10:11], s[12:13], s[10:11]
	v_cmp_gt_i32_e64 s[6:7], 33, v100
	s_and_b64 s[8:9], s[10:11], s[8:9]
	v_cmp_gt_i32_e32 vcc, 32, v100
	s_and_b64 s[6:7], s[8:9], s[6:7]
	s_and_b64 vcc, s[6:7], vcc
	v_cndmask_b32_e64 v97, v97, v186, s[66:67]
	v_cndmask_b32_e64 v96, v96, v186, s[64:65]
	v_cndmask_b32_e64 v95, v95, v186, s[62:63]
	v_cndmask_b32_e64 v94, v94, v186, s[60:61]
	v_cndmask_b32_e64 v93, v93, v186, s[58:59]
	v_cndmask_b32_e64 v92, v92, v186, s[56:57]
	v_cndmask_b32_e64 v91, v91, v186, s[54:55]
	v_cndmask_b32_e64 v90, v90, v186, s[52:53]
	v_cndmask_b32_e64 v89, v89, v186, s[50:51]
	v_cndmask_b32_e64 v88, v88, v186, s[48:49]
	v_cndmask_b32_e64 v87, v87, v186, s[46:47]
	v_cndmask_b32_e64 v86, v86, v186, s[44:45]
	v_cndmask_b32_e64 v85, v85, v186, s[42:43]
	v_cndmask_b32_e64 v84, v84, v186, s[40:41]
	v_cndmask_b32_e64 v83, v83, v186, s[38:39]
	v_cndmask_b32_e64 v81, v81, v186, s[36:37]
	v_cndmask_b32_e64 v80, v80, v186, s[34:35]
	v_cndmask_b32_e64 v79, v79, v186, s[30:31]
	v_cndmask_b32_e64 v78, v78, v186, s[28:29]
	v_cndmask_b32_e64 v77, v77, v186, s[26:27]
	v_cndmask_b32_e64 v76, v76, v186, s[24:25]
	v_cndmask_b32_e64 v75, v75, v186, s[22:23]
	v_cndmask_b32_e64 v74, v74, v186, s[20:21]
	v_cndmask_b32_e64 v73, v73, v186, s[18:19]
	v_cndmask_b32_e64 v72, v72, v186, s[16:17]
	v_cndmask_b32_e64 v71, v71, v186, s[14:15]
	v_cndmask_b32_e64 v70, v70, v186, s[12:13]
	v_cndmask_b32_e64 v69, v69, v186, s[10:11]
	v_cndmask_b32_e64 v68, v68, v186, s[8:9]
	v_cndmask_b32_e64 v67, v67, v186, s[6:7]
	v_cndmask_b32_e32 v66, v66, v186, vcc

; __device__ __forceinline__ void partialSM(f32x16& p0, f32x16& p1, float& m_reg, float& mn, float& alpha) {
;     ...
;     else { mn = fmaxf(m_reg, pmax); alpha = __builtin_amdgcn_exp2f((m_reg - mn) * C2); m_reg = mn; }
;     const float mnL = -mn * C2;
; #pragma unroll
;     for (int r = 0; r < 16; ++r) p0[r] = fmaf(p0[r], C2, mnL);
; #pragma unroll
;     for (int r = 0; r < 16; ++r) p1[r] = fmaf(p1[r], C2, mnL);
; #pragma unroll
;     for (int r = 0; r < 16; ++r) p0[r] = __builtin_amdgcn_exp2f(p0[r]);
; }
; __device__ __forceinline__ void finishSM(f32x16& p0, f32x16& p1, float alpha, float& l_reg, bf16x8& pa0, bf16x8& pa1, bf16x8& pa2, bf16x8& pa3) {
; #pragma unroll
;     for (int r = 0; r < 16; ++r) p1[r] = __builtin_amdgcn_exp2f(p1[r]);
;     float ps = 0;
; #pragma unroll
;     for (int r = 0; r < 16; ++r) ps += p0[r];
; #pragma unroll
;     for (int r = 0; r < 16; ++r) ps += p1[r];
;     { auto rr = __builtin_amdgcn_permlane32_swap(__float_as_uint(ps), __float_as_uint(ps), false, false);
;       ps = __uint_as_float(rr[0]) + __uint_as_float(rr[1]); }
;     l_reg = l_reg * alpha + ps;
;     ...
;     PK4(p0, 0, pa0); PK4(p0, 8, pa1); PK4(p1, 0, pa2); PK4(p1, 8, pa3);
;     ...
; }
; template <int VB>
; __device__ __forceinline__ void pv_tile(f32x16* o, int vb0, bf16x8 pa0, bf16x8 pa1, bf16x8 pa2, bf16x8 pa3) {
;     ...
;     PV_D0(0); PV_D0(1); PV_D0(2); PV_D0(3);
.LBB0_432:
	v_cndmask_b32_e64 v101, v101, v210, s[6:7]
	v_mul_f32_e32 v101, 0xbdd53b94, v101
	v_fmamk_f32 v82, v82, 0x3dd53b94, v101
	v_fmamk_f32 v83, v83, 0x3dd53b94, v101
	v_fmamk_f32 v102, v84, 0x3dd53b94, v101
	v_exp_f32_e32 v84, v82
	v_fmamk_f32 v103, v86, 0x3dd53b94, v101
	v_exp_f32_e32 v86, v83
	v_fmamk_f32 v85, v85, 0x3dd53b94, v101
	v_exp_f32_e32 v82, v102
	v_fmamk_f32 v66, v66, 0x3dd53b94, v101
	v_exp_f32_e32 v85, v85
	v_fmamk_f32 v104, v87, 0x3dd53b94, v101
	v_fmamk_f32 v113, v96, 0x3dd53b94, v101
	v_fmamk_f32 v96, v77, 0x3dd53b94, v101
	v_exp_f32_e32 v77, v103
	v_exp_f32_e32 v102, v66
	v_add_f32_e32 v66, 0, v84
	v_fmamk_f32 v105, v88, 0x3dd53b94, v101
	v_exp_f32_e32 v83, v104
	v_add_f32_e32 v66, v86, v66
	v_fmamk_f32 v106, v89, 0x3dd53b94, v101
	v_fmamk_f32 v112, v95, 0x3dd53b94, v101
	v_fmamk_f32 v95, v76, 0x3dd53b94, v101
	v_exp_f32_e32 v76, v105
	v_add_f32_e32 v66, v82, v66
	v_fmamk_f32 v107, v90, 0x3dd53b94, v101
	v_fmamk_f32 v114, v97, 0x3dd53b94, v101
	v_fmamk_f32 v97, v78, 0x3dd53b94, v101
	v_exp_f32_e32 v78, v106
	v_add_f32_e32 v66, v85, v66
	v_fmamk_f32 v108, v91, 0x3dd53b94, v101
	v_fmamk_f32 v109, v92, 0x3dd53b94, v101
	v_fmamk_f32 v92, v73, 0x3dd53b94, v101
	v_exp_f32_e32 v73, v107
	v_add_f32_e32 v66, v77, v66
	v_fmamk_f32 v111, v94, 0x3dd53b94, v101
	v_fmamk_f32 v94, v75, 0x3dd53b94, v101
	v_exp_f32_e32 v75, v108
	v_add_f32_e32 v66, v83, v66
	v_fmamk_f32 v110, v93, 0x3dd53b94, v101
	v_fmamk_f32 v90, v71, 0x3dd53b94, v101
	v_exp_f32_e32 v71, v109
	v_add_f32_e32 v66, v76, v66
	v_fmamk_f32 v93, v74, 0x3dd53b94, v101
	v_exp_f32_e32 v74, v110
	v_add_f32_e32 v66, v78, v66
	v_fmamk_f32 v88, v69, 0x3dd53b94, v101
	v_exp_f32_e32 v69, v111
	v_add_f32_e32 v66, v73, v66
	v_fmamk_f32 v91, v72, 0x3dd53b94, v101
	v_exp_f32_e32 v72, v112
	v_add_f32_e32 v66, v75, v66
	v_fmamk_f32 v87, v68, 0x3dd53b94, v101
	v_exp_f32_e32 v68, v113
	v_add_f32_e32 v66, v71, v66
	v_fmamk_f32 v89, v70, 0x3dd53b94, v101
	v_exp_f32_e32 v70, v114
	v_add_f32_e32 v66, v74, v66
	v_fmamk_f32 v67, v67, 0x3dd53b94, v101
	v_add_f32_e32 v66, v69, v66
	v_exp_f32_e32 v103, v67
	v_add_f32_e32 v66, v72, v66
	v_exp_f32_e32 v87, v87
	v_add_f32_e32 v66, v68, v66
	v_exp_f32_e32 v88, v88
	v_add_f32_e32 v66, v70, v66
	v_exp_f32_e32 v89, v89
	v_add_f32_e32 v66, v102, v66
	v_exp_f32_e32 v90, v90
	v_add_f32_e32 v66, v103, v66
	v_exp_f32_e32 v91, v91
	v_add_f32_e32 v66, v87, v66
	v_exp_f32_e32 v92, v92
	v_add_f32_e32 v66, v88, v66
	v_exp_f32_e32 v93, v93
	v_add_f32_e32 v66, v89, v66
	v_exp_f32_e32 v94, v94
	v_add_f32_e32 v66, v90, v66
	v_exp_f32_e32 v95, v95
	v_add_f32_e32 v66, v91, v66
	v_exp_f32_e32 v96, v96
	v_add_f32_e32 v66, v92, v66
	v_fmamk_f32 v79, v79, 0x3dd53b94, v101
	v_exp_f32_e32 v97, v97
	v_add_f32_e32 v66, v93, v66
	v_fmamk_f32 v80, v80, 0x3dd53b94, v101
	v_exp_f32_e32 v104, v79
	v_add_f32_e32 v66, v94, v66
	v_fmac_f32_e32 v101, 0x3dd53b94, v81
	v_exp_f32_e32 v105, v80
	v_add_f32_e32 v66, v95, v66
	v_exp_f32_e32 v101, v101
	v_add_f32_e32 v66, v96, v66
	v_add_f32_e32 v66, v97, v66
	v_add_f32_e32 v66, v104, v66
	v_add_f32_e32 v66, v105, v66
	v_add_f32_e32 v66, v101, v66
	v_mov_b32_e32 v67, v66
	s_nop 1
	v_permlane32_swap_b32_e32 v66, v67
	v_cvt_pk_bf16_f32 v80, v84, v86
	v_cvt_pk_bf16_f32 v81, v82, v85
	v_cvt_pk_bf16_f32 v82, v77, v83
	v_cvt_pk_bf16_f32 v83, v76, v78
	v_cvt_pk_bf16_f32 v76, v73, v75
	v_cvt_pk_bf16_f32 v77, v71, v74
	v_cvt_pk_bf16_f32 v78, v69, v72
	v_cvt_pk_bf16_f32 v79, v68, v70
	v_cvt_pk_bf16_f32 v68, v102, v103
	v_cvt_pk_bf16_f32 v69, v87, v88
	v_cvt_pk_bf16_f32 v70, v89, v90
	v_cvt_pk_bf16_f32 v71, v91, v92
	v_cvt_pk_bf16_f32 v72, v93, v94
	v_cvt_pk_bf16_f32 v73, v95, v96
	v_cvt_pk_bf16_f32 v74, v97, v104
	v_cvt_pk_bf16_f32 v75, v105, v101
	s_nop 0
	v_permlane32_swap_b32_e32 v80, v82
	v_permlane32_swap_b32_e32 v81, v83
	v_permlane32_swap_b32_e32 v76, v78
	v_permlane32_swap_b32_e32 v77, v79
	v_permlane32_swap_b32_e32 v68, v70
	v_permlane32_swap_b32_e32 v69, v71
	v_permlane32_swap_b32_e32 v72, v74
	v_permlane32_swap_b32_e32 v73, v75
	ds_read_b64_tr_b16 v[84:85], v194 offset:0x4000
	ds_read_b64_tr_b16 v[86:87], v194 offset:0x4800
	ds_read_b64_tr_b16 v[88:89], v194 offset:0x5000
	ds_read_b64_tr_b16 v[90:91], v194 offset:0x5800
	ds_read_b64_tr_b16 v[92:93], v194 offset:0x6000
	ds_read_b64_tr_b16 v[94:95], v194 offset:0x6800
	ds_read_b64_tr_b16 v[102:103], v194 offset:0x7000
	ds_read_b64_tr_b16 v[104:105], v194 offset:0x7800
	s_nop 0
	s_waitcnt lgkmcnt(6)
	v_mfma_f32_32x32x16_bf16 v[50:65], v[80:83], v[84:87], v[50:65]
	ds_read_b64_tr_b16 v[84:85], v194 offset:0x4200
	ds_read_b64_tr_b16 v[86:87], v194 offset:0x4a00
	s_waitcnt lgkmcnt(6)
	v_mfma_f32_32x32x16_bf16 v[50:65], v[76:79], v[88:91], v[50:65]
	ds_read_b64_tr_b16 v[88:89], v194 offset:0x5200
	ds_read_b64_tr_b16 v[90:91], v194 offset:0x5a00
	s_waitcnt lgkmcnt(6)
	v_mfma_f32_32x32x16_bf16 v[50:65], v[68:71], v[92:95], v[50:65]
	ds_read_b64_tr_b16 v[92:93], v194 offset:0x6200
	ds_read_b64_tr_b16 v[94:95], v194 offset:0x6a00
	s_waitcnt lgkmcnt(6)
; __device__ __forceinline__ unsigned cvtpk(float lo, float hi) { unsigned r; asm("v_cvt_pk_bf16_f32 %0, %1, %2" : "=v"(r) : "v"(lo), "v"(hi)); return r; }
; #define SBAR() __builtin_amdgcn_sched_barrier(0)
; __device__ __forceinline__ int crow(int r, int hi) { return (r & 3) + 8 * (r >> 2) + 4 * hi; }
; template <int VB>
; __device__ __forceinline__ void pv_tile(f32x16* o, int vb0, bf16x8 pa0, bf16x8 pa1, bf16x8 pa2, bf16x8 pa3) {
;     ...
;     PV_D0(0); PV_D0(1); PV_D0(2); PV_D0(3);
; __device__ __forceinline__ void attn_block(const ABlk& cur, char* lds, ASeam& Sm, const int tid, const int wv) {
;     ...
;     finishSM(pB0, pB1, alB, l_reg, pa0, pa1, pa2, pa3); SBAR(); pv_tile<1>(o, vb0, pa0, pa1, pa2, pa3);
;     SBAR();
;     if (hi == 0) li_l[r32] = l_reg; asm volatile("s_waitcnt lgkmcnt(0)" ::: "memory");
;     const int tid_e = opq_tid(wv);
;     const int e32 = tid_e & 31, ehi = (tid_e >> 5) & 1, ewid = tid_e >> 6;
;     u32x4 gw[8];
; #pragma unroll
;     for (int k = 0; k < 8; ++k) gw[k] = *(const u32x4*)(cur.G + (size_t)((tid_e >> 4) + 32 * k) * 2048 + (tid_e & 15) * 8);
;     float rli[16];
; #pragma unroll
;     for (int r = 0; r < 16; ++r) rli[r] = __builtin_amdgcn_rcpf(li_l[crow(r, ehi)]);
;     __syncthreads();
;     constexpr int OPITCH = 272;
; #pragma unroll
;     for (int r = 0; r < 16; ++r) { char* srow = lds + (ewid * QBLK + crow(r, ehi)) * OPITCH + e32 * 2;
; #pragma unroll
;         for (int d0 = 0; d0 < 4; ++d0) { const float v = o[d0][r] * rli[r];
;             const float vn = __int_as_float(__builtin_amdgcn_update_dpp(0, __float_as_int(v), 0xB1, 0xF, 0xF, true));
;             if ((e32 & 1) == 0) *(unsigned*)(srow + d0 * 64) = cvtpk(v, vn); } }
	v_mfma_f32_32x32x16_bf16 v[50:65], v[72:75], v[102:105], v[50:65]
	ds_read_b64_tr_b16 v[102:103], v194 offset:0x7200
	ds_read_b64_tr_b16 v[104:105], v194 offset:0x7a00
	s_waitcnt lgkmcnt(6)
	v_mfma_f32_32x32x16_bf16 v[34:49], v[80:83], v[84:87], v[34:49]
	ds_read_b64_tr_b16 v[84:85], v194 offset:0x4400
	ds_read_b64_tr_b16 v[86:87], v194 offset:0x4c00
	s_waitcnt lgkmcnt(6)
	v_mfma_f32_32x32x16_bf16 v[34:49], v[76:79], v[88:91], v[34:49]
	ds_read_b64_tr_b16 v[88:89], v194 offset:0x5400
	ds_read_b64_tr_b16 v[90:91], v194 offset:0x5c00
	s_waitcnt lgkmcnt(6)
	v_mfma_f32_32x32x16_bf16 v[34:49], v[68:71], v[92:95], v[34:49]
	ds_read_b64_tr_b16 v[92:93], v194 offset:0x6400
	ds_read_b64_tr_b16 v[94:95], v194 offset:0x6c00
	s_waitcnt lgkmcnt(6)
	v_mfma_f32_32x32x16_bf16 v[34:49], v[72:75], v[102:105], v[34:49]
	ds_read_b64_tr_b16 v[102:103], v194 offset:0x7400
	ds_read_b64_tr_b16 v[104:105], v194 offset:0x7c00
	s_waitcnt lgkmcnt(6)
	v_mfma_f32_32x32x16_bf16 v[18:33], v[80:83], v[84:87], v[18:33]
	ds_read_b64_tr_b16 v[84:85], v194 offset:0x4600
	ds_read_b64_tr_b16 v[86:87], v194 offset:0x4e00
	s_waitcnt lgkmcnt(6)
	v_mfma_f32_32x32x16_bf16 v[18:33], v[76:79], v[88:91], v[18:33]
	ds_read_b64_tr_b16 v[88:89], v194 offset:0x5600
	ds_read_b64_tr_b16 v[90:91], v194 offset:0x5e00
	s_waitcnt lgkmcnt(6)
	v_mfma_f32_32x32x16_bf16 v[18:33], v[68:71], v[92:95], v[18:33]
	ds_read_b64_tr_b16 v[92:93], v194 offset:0x6600
	ds_read_b64_tr_b16 v[94:95], v194 offset:0x6e00
	s_waitcnt lgkmcnt(6)
	v_mfma_f32_32x32x16_bf16 v[18:33], v[72:75], v[102:105], v[18:33]
	ds_read_b64_tr_b16 v[102:103], v194 offset:0x7600
	ds_read_b64_tr_b16 v[104:105], v194 offset:0x7e00
	s_waitcnt lgkmcnt(6)
	v_mfma_f32_32x32x16_bf16 v[2:17], v[80:83], v[84:87], v[2:17]
	s_waitcnt lgkmcnt(4)
	v_mfma_f32_32x32x16_bf16 v[2:17], v[76:79], v[88:91], v[2:17]
	s_waitcnt lgkmcnt(2)
	v_mfma_f32_32x32x16_bf16 v[2:17], v[68:71], v[92:95], v[2:17]
	s_waitcnt lgkmcnt(0)
	v_mfma_f32_32x32x16_bf16 v[2:17], v[72:75], v[102:105], v[2:17]
	s_and_saveexec_b64 s[6:7], s[4:5]
	v_add_f32_e32 v68, v98, v99
	v_fmac_f32_e32 v68, v196, v0
	v_add_f32_e32 v0, v66, v67
	v_fmac_f32_e32 v0, v68, v100
	ds_write_b32 v195, v0
	s_or_b64 exec, exec, s[6:7]
	v_readlane_b32 s4, v255, 1
	v_mov_b32_e32 v0, v1
	v_readlane_b32 s5, v255, 2
	s_add_u32 s2, s2, s4
	s_waitcnt lgkmcnt(0)
	s_addc_u32 s3, s3, s5
	s_lshl_b32 s4, s72, 20
	v_mbcnt_lo_u32_b32 v0, -1, v0
	s_add_u32 s2, s2, s4
	v_mbcnt_hi_u32_b32 v0, -1, v0
	s_addc_u32 s3, s3, 0
	v_readlane_b32 s4, v255, 17
	v_or_b32_e32 v132, s57, v0
	v_readlane_b32 s5, v255, 18
	s_add_u32 s2, s2, s4
	s_addc_u32 s3, s3, s5
	v_ashrrev_i32_e32 v130, 4, v132
	v_ashrrev_i32_e32 v131, 31, v130
	s_add_u32 s2, s2, 0xcc00000
	v_lshlrev_b32_e32 v0, 4, v132
	v_lshlrev_b64 v[128:129], 12, v[130:131]
	s_mov_b64 s[4:5], 0x60000
	s_addc_u32 s3, s3, 0
	v_and_b32_e32 v0, 0xf0, v0
	v_lshl_add_u64 v[122:123], v[128:129], 0, s[4:5]
	s_mov_b64 s[4:5], 0x80000
	v_lshl_add_u64 v[66:67], s[2:3], 0, v[0:1]
	v_lshl_add_u64 v[120:121], v[128:129], 0, s[4:5]
	s_mov_b64 s[4:5], 0xa0000
	v_lshl_add_u64 v[68:69], v[66:67], 0, v[128:129]
	v_lshl_add_u64 v[126:127], v[128:129], 0, s[78:79]
	v_lshl_add_u64 v[124:125], v[128:129], 0, s[68:69]
	v_lshl_add_u64 v[118:119], v[128:129], 0, s[4:5]
	s_mov_b64 s[4:5], 0xc0000
	v_lshl_add_u64 v[70:71], v[66:67], 0, v[126:127]
	global_load_dwordx4 v[94:97], v[68:69], off
	global_load_dwordx4 v[90:93], v[70:71], off
	v_lshl_add_u64 v[68:69], v[66:67], 0, v[124:125]
	v_lshl_add_u64 v[116:117], v[128:129], 0, s[4:5]
	s_mov_b64 s[4:5], 0xe0000
	v_lshl_add_u64 v[70:71], v[66:67], 0, v[122:123]
	global_load_dwordx4 v[86:89], v[68:69], off
	global_load_dwordx4 v[82:85], v[70:71], off
	v_lshl_add_u64 v[68:69], v[66:67], 0, v[120:121]
	v_lshl_add_u64 v[114:115], v[128:129], 0, s[4:5]
	v_lshl_add_u64 v[70:71], v[66:67], 0, v[118:119]
	global_load_dwordx4 v[78:81], v[68:69], off
	global_load_dwordx4 v[74:77], v[70:71], off
	v_lshl_add_u64 v[68:69], v[66:67], 0, v[116:117]
	v_lshl_add_u64 v[66:67], v[66:67], 0, v[114:115]
	global_load_dwordx4 v[70:73], v[68:69], off
	s_nop 0
	global_load_dwordx4 v[66:69], v[66:67], off
	v_bfe_u32 v133, v132, 5, 1
	v_lshl_add_u32 v98, v133, 4, s71
	ds_read_b128 v[110:113], v98
	ds_read_b128 v[106:109], v98 offset:32
	ds_read_b128 v[102:105], v98 offset:64
	ds_read_b128 v[98:101], v98 offset:96
	s_waitcnt lgkmcnt(0)
	s_barrier
	v_rcp_f32_e32 v131, v110
	v_lshrrev_b32_e32 v110, 1, v132
	v_and_b32_e32 v110, 0xfffffe0, v110
	v_lshl_or_b32 v110, v133, 2, v110
	v_lshlrev_b32_e32 v133, 1, v132
	v_and_b32_e32 v133, 62, v133
	v_and_b32_e32 v132, 1, v132
	v_mul_lo_u32 v110, v110, s12
	v_mul_f32_e32 v50, v50, v131
	v_cmp_eq_u32_e32 vcc, 0, v132
	v_add3_u32 v110, 0, v133, v110
	v_mov_b32_dpp v132, v50 quad_perm:[1,0,3,2] row_mask:0xf bank_mask:0xf bound_ctrl:1
	s_and_saveexec_b64 s[4:5], vcc
	s_cbranch_execz .LBB0_436
	v_cvt_pk_bf16_f32 v50, v50, v132
	ds_write_b32 v110, v50
